# HGRN: next super-group staging merged into the last group's barrier (one workgroup barrier fewer per 128 steps)
# baseline (speedup 1.0000x reference)
.Lhg_go:
	s_lshl_b32 s41, s40, 12
	s_add_i32 s41, s41, s18
	v_mov_b32_e32 v124, s41
	v_add_u32_e32 v125, 0x12000, v50
	v_lshl_add_u32 v51, s40, 15, v34
	ds_read_b128 v[52:55], v124 offset:0
	ds_read_b128 v[56:59], v124 offset:16
	ds_read_b128 v[60:63], v124 offset:32
	ds_read_b128 v[64:67], v124 offset:48
	ds_read_b128 v[68:71], v124 offset:64
	ds_read_b128 v[72:75], v124 offset:80
	ds_read_b128 v[76:79], v124 offset:96
	ds_read_b128 v[80:83], v124 offset:112
	s_waitcnt lgkmcnt(0)
	v_lshlrev_b32_e32 v126, 16, v116
	v_pk_add_f32 v[130:131], v[26:27], v[126:127] op_sel_hi:[1,0] neg_lo:[0,1] neg_hi:[0,1]
	v_pk_add_f32 v[132:133], v[24:25], v[126:127] op_sel_hi:[1,0] neg_lo:[0,1] neg_hi:[0,1]
	v_lshlrev_b32_e32 v128, 16, v117
	v_pk_fma_f32 v[26:27], v[130:131], v[52:53], v[126:127] op_sel_hi:[1,1,0]
	v_pk_fma_f32 v[24:25], v[132:133], v[54:55], v[126:127] op_sel_hi:[1,1,0]
	ds_read_u16 v120, v125 offset:512
	ds_read_u16 v121, v125 offset:640
	ds_read_u16 v122, v125 offset:768
	ds_read_u16 v123, v125 offset:896
	ds_read_b128 v[84:87], v124 offset:128
	ds_read_b128 v[88:91], v124 offset:144
	ds_read_b128 v[92:95], v124 offset:160
	ds_read_b128 v[96:99], v124 offset:176
	ds_read_b128 v[100:103], v124 offset:192
	ds_read_b128 v[104:107], v124 offset:208
	ds_read_b128 v[108:111], v124 offset:224
	ds_read_b128 v[112:115], v124 offset:240
	v_pk_mul_f32 v[134:135], v[58:59], v[24:25]
	v_pk_add_f32 v[130:131], v[26:27], v[128:129] op_sel_hi:[1,0] neg_lo:[0,1] neg_hi:[0,1]
	v_pk_add_f32 v[132:133], v[24:25], v[128:129] op_sel_hi:[1,0] neg_lo:[0,1] neg_hi:[0,1]
	v_lshlrev_b32_e32 v126, 16, v118
	v_pk_fma_f32 v[134:135], v[56:57], v[26:27], v[134:135]
	v_pk_fma_f32 v[26:27], v[130:131], v[60:61], v[128:129] op_sel_hi:[1,1,0]
	v_pk_fma_f32 v[24:25], v[132:133], v[62:63], v[128:129] op_sel_hi:[1,1,0]
	v_add_f32_e32 v136, v134, v135
	v_pk_mul_f32 v[134:135], v[66:67], v[24:25]
	v_pk_add_f32 v[130:131], v[26:27], v[126:127] op_sel_hi:[1,0] neg_lo:[0,1] neg_hi:[0,1]
	v_pk_add_f32 v[132:133], v[24:25], v[126:127] op_sel_hi:[1,0] neg_lo:[0,1] neg_hi:[0,1]
	v_lshlrev_b32_e32 v128, 16, v119
	v_pk_fma_f32 v[134:135], v[64:65], v[26:27], v[134:135]
	v_pk_fma_f32 v[26:27], v[130:131], v[68:69], v[126:127] op_sel_hi:[1,1,0]
	v_pk_fma_f32 v[24:25], v[132:133], v[70:71], v[126:127] op_sel_hi:[1,1,0]
	v_add_f32_e32 v137, v134, v135
	ds_write2st64_b32 v51, v136, v137 offset0:32 offset1:33
	v_pk_mul_f32 v[134:135], v[74:75], v[24:25]
	v_pk_add_f32 v[130:131], v[26:27], v[128:129] op_sel_hi:[1,0] neg_lo:[0,1] neg_hi:[0,1]
	v_pk_add_f32 v[132:133], v[24:25], v[128:129] op_sel_hi:[1,0] neg_lo:[0,1] neg_hi:[0,1]
	v_pk_fma_f32 v[134:135], v[72:73], v[26:27], v[134:135]
	v_pk_fma_f32 v[26:27], v[130:131], v[76:77], v[128:129] op_sel_hi:[1,1,0]
	v_pk_fma_f32 v[24:25], v[132:133], v[78:79], v[128:129] op_sel_hi:[1,1,0]
	v_add_f32_e32 v138, v134, v135
	s_waitcnt lgkmcnt(1)
	v_lshlrev_b32_e32 v126, 16, v120
	v_pk_mul_f32 v[134:135], v[82:83], v[24:25]
	v_pk_add_f32 v[130:131], v[26:27], v[126:127] op_sel_hi:[1,0] neg_lo:[0,1] neg_hi:[0,1]
	v_pk_add_f32 v[132:133], v[24:25], v[126:127] op_sel_hi:[1,0] neg_lo:[0,1] neg_hi:[0,1]
	v_lshlrev_b32_e32 v128, 16, v121
	v_pk_fma_f32 v[134:135], v[80:81], v[26:27], v[134:135]
	v_pk_fma_f32 v[26:27], v[130:131], v[84:85], v[126:127] op_sel_hi:[1,1,0]
	v_pk_fma_f32 v[24:25], v[132:133], v[86:87], v[126:127] op_sel_hi:[1,1,0]
	v_add_f32_e32 v139, v134, v135
	ds_write2st64_b32 v51, v138, v139 offset0:34 offset1:35
	ds_read_u16 v116, v125 offset:1024
	ds_read_u16 v117, v125 offset:1152
	ds_read_u16 v118, v125 offset:1280
	ds_read_u16 v119, v125 offset:1408
	ds_read_b128 v[52:55], v124 offset:256
	ds_read_b128 v[56:59], v124 offset:272
	ds_read_b128 v[60:63], v124 offset:288
	ds_read_b128 v[64:67], v124 offset:304
	ds_read_b128 v[68:71], v124 offset:320
	ds_read_b128 v[72:75], v124 offset:336
	ds_read_b128 v[76:79], v124 offset:352
	ds_read_b128 v[80:83], v124 offset:368
	v_pk_mul_f32 v[134:135], v[90:91], v[24:25]
	v_pk_add_f32 v[130:131], v[26:27], v[128:129] op_sel_hi:[1,0] neg_lo:[0,1] neg_hi:[0,1]
	v_pk_add_f32 v[132:133], v[24:25], v[128:129] op_sel_hi:[1,0] neg_lo:[0,1] neg_hi:[0,1]
	v_lshlrev_b32_e32 v126, 16, v122
	v_pk_fma_f32 v[134:135], v[88:89], v[26:27], v[134:135]
	v_pk_fma_f32 v[26:27], v[130:131], v[92:93], v[128:129] op_sel_hi:[1,1,0]
	v_pk_fma_f32 v[24:25], v[132:133], v[94:95], v[128:129] op_sel_hi:[1,1,0]
	v_add_f32_e32 v136, v134, v135
	v_pk_mul_f32 v[134:135], v[98:99], v[24:25]
	v_pk_add_f32 v[130:131], v[26:27], v[126:127] op_sel_hi:[1,0] neg_lo:[0,1] neg_hi:[0,1]
	v_pk_add_f32 v[132:133], v[24:25], v[126:127] op_sel_hi:[1,0] neg_lo:[0,1] neg_hi:[0,1]
	v_lshlrev_b32_e32 v128, 16, v123
	v_pk_fma_f32 v[134:135], v[96:97], v[26:27], v[134:135]
	v_pk_fma_f32 v[26:27], v[130:131], v[100:101], v[126:127] op_sel_hi:[1,1,0]
	v_pk_fma_f32 v[24:25], v[132:133], v[102:103], v[126:127] op_sel_hi:[1,1,0]
	v_add_f32_e32 v137, v134, v135
	ds_write2st64_b32 v51, v136, v137 offset0:36 offset1:37
	v_pk_mul_f32 v[134:135], v[106:107], v[24:25]
	v_pk_add_f32 v[130:131], v[26:27], v[128:129] op_sel_hi:[1,0] neg_lo:[0,1] neg_hi:[0,1]
	v_pk_add_f32 v[132:133], v[24:25], v[128:129] op_sel_hi:[1,0] neg_lo:[0,1] neg_hi:[0,1]
	v_pk_fma_f32 v[134:135], v[104:105], v[26:27], v[134:135]
	v_pk_fma_f32 v[26:27], v[130:131], v[108:109], v[128:129] op_sel_hi:[1,1,0]
	v_pk_fma_f32 v[24:25], v[132:133], v[110:111], v[128:129] op_sel_hi:[1,1,0]
	v_add_f32_e32 v138, v134, v135
	s_waitcnt lgkmcnt(1)
	v_lshlrev_b32_e32 v126, 16, v116
	v_pk_mul_f32 v[134:135], v[114:115], v[24:25]
	v_pk_add_f32 v[130:131], v[26:27], v[126:127] op_sel_hi:[1,0] neg_lo:[0,1] neg_hi:[0,1]
	v_pk_add_f32 v[132:133], v[24:25], v[126:127] op_sel_hi:[1,0] neg_lo:[0,1] neg_hi:[0,1]
	v_lshlrev_b32_e32 v128, 16, v117
	v_pk_fma_f32 v[134:135], v[112:113], v[26:27], v[134:135]
	v_pk_fma_f32 v[26:27], v[130:131], v[52:53], v[126:127] op_sel_hi:[1,1,0]
	v_pk_fma_f32 v[24:25], v[132:133], v[54:55], v[126:127] op_sel_hi:[1,1,0]
	v_add_f32_e32 v139, v134, v135
	ds_write2st64_b32 v51, v138, v139 offset0:38 offset1:39
	ds_read_u16 v120, v125 offset:1536
	ds_read_u16 v121, v125 offset:1664
	ds_read_u16 v122, v125 offset:1792
	ds_read_u16 v123, v125 offset:1920
	ds_read_b128 v[84:87], v124 offset:384
	ds_read_b128 v[88:91], v124 offset:400
	ds_read_b128 v[92:95], v124 offset:416
	ds_read_b128 v[96:99], v124 offset:432
	ds_read_b128 v[100:103], v124 offset:448
	ds_read_b128 v[104:107], v124 offset:464
	ds_read_b128 v[108:111], v124 offset:480
	ds_read_b128 v[112:115], v124 offset:496
	v_pk_mul_f32 v[134:135], v[58:59], v[24:25]
	v_pk_add_f32 v[130:131], v[26:27], v[128:129] op_sel_hi:[1,0] neg_lo:[0,1] neg_hi:[0,1]
	v_pk_add_f32 v[132:133], v[24:25], v[128:129] op_sel_hi:[1,0] neg_lo:[0,1] neg_hi:[0,1]
	v_lshlrev_b32_e32 v126, 16, v118
	v_pk_fma_f32 v[134:135], v[56:57], v[26:27], v[134:135]
	v_pk_fma_f32 v[26:27], v[130:131], v[60:61], v[128:129] op_sel_hi:[1,1,0]
	v_pk_fma_f32 v[24:25], v[132:133], v[62:63], v[128:129] op_sel_hi:[1,1,0]
	v_add_f32_e32 v136, v134, v135
	v_pk_mul_f32 v[134:135], v[66:67], v[24:25]
	v_pk_add_f32 v[130:131], v[26:27], v[126:127] op_sel_hi:[1,0] neg_lo:[0,1] neg_hi:[0,1]
	v_pk_add_f32 v[132:133], v[24:25], v[126:127] op_sel_hi:[1,0] neg_lo:[0,1] neg_hi:[0,1]
	v_lshlrev_b32_e32 v128, 16, v119
	v_pk_fma_f32 v[134:135], v[64:65], v[26:27], v[134:135]
	v_pk_fma_f32 v[26:27], v[130:131], v[68:69], v[126:127] op_sel_hi:[1,1,0]
	v_pk_fma_f32 v[24:25], v[132:133], v[70:71], v[126:127] op_sel_hi:[1,1,0]
	v_add_f32_e32 v137, v134, v135
	ds_write2st64_b32 v51, v136, v137 offset0:40 offset1:41
	v_pk_mul_f32 v[134:135], v[74:75], v[24:25]
	v_pk_add_f32 v[130:131], v[26:27], v[128:129] op_sel_hi:[1,0] neg_lo:[0,1] neg_hi:[0,1]
	v_pk_add_f32 v[132:133], v[24:25], v[128:129] op_sel_hi:[1,0] neg_lo:[0,1] neg_hi:[0,1]
	v_pk_fma_f32 v[134:135], v[72:73], v[26:27], v[134:135]
	v_pk_fma_f32 v[26:27], v[130:131], v[76:77], v[128:129] op_sel_hi:[1,1,0]
	v_pk_fma_f32 v[24:25], v[132:133], v[78:79], v[128:129] op_sel_hi:[1,1,0]
	v_add_f32_e32 v138, v134, v135
	s_waitcnt lgkmcnt(1)
	v_lshlrev_b32_e32 v126, 16, v120
	v_pk_mul_f32 v[134:135], v[82:83], v[24:25]
	v_pk_add_f32 v[130:131], v[26:27], v[126:127] op_sel_hi:[1,0] neg_lo:[0,1] neg_hi:[0,1]
	v_pk_add_f32 v[132:133], v[24:25], v[126:127] op_sel_hi:[1,0] neg_lo:[0,1] neg_hi:[0,1]
	v_lshlrev_b32_e32 v128, 16, v121
	v_pk_fma_f32 v[134:135], v[80:81], v[26:27], v[134:135]
	v_pk_fma_f32 v[26:27], v[130:131], v[84:85], v[126:127] op_sel_hi:[1,1,0]
	v_pk_fma_f32 v[24:25], v[132:133], v[86:87], v[126:127] op_sel_hi:[1,1,0]
	v_add_f32_e32 v139, v134, v135
	ds_write2st64_b32 v51, v138, v139 offset0:42 offset1:43
	ds_read_u16 v116, v125 offset:2048
	ds_read_u16 v117, v125 offset:2176
	ds_read_u16 v118, v125 offset:2304
	ds_read_u16 v119, v125 offset:2432
	ds_read_b128 v[52:55], v124 offset:512
	ds_read_b128 v[56:59], v124 offset:528
	ds_read_b128 v[60:63], v124 offset:544
	ds_read_b128 v[64:67], v124 offset:560
	ds_read_b128 v[68:71], v124 offset:576
	ds_read_b128 v[72:75], v124 offset:592
	ds_read_b128 v[76:79], v124 offset:608
	ds_read_b128 v[80:83], v124 offset:624
	v_pk_mul_f32 v[134:135], v[90:91], v[24:25]
	v_pk_add_f32 v[130:131], v[26:27], v[128:129] op_sel_hi:[1,0] neg_lo:[0,1] neg_hi:[0,1]
	v_pk_add_f32 v[132:133], v[24:25], v[128:129] op_sel_hi:[1,0] neg_lo:[0,1] neg_hi:[0,1]
	v_lshlrev_b32_e32 v126, 16, v122
	v_pk_fma_f32 v[134:135], v[88:89], v[26:27], v[134:135]
	v_pk_fma_f32 v[26:27], v[130:131], v[92:93], v[128:129] op_sel_hi:[1,1,0]
	v_pk_fma_f32 v[24:25], v[132:133], v[94:95], v[128:129] op_sel_hi:[1,1,0]
	v_add_f32_e32 v136, v134, v135
	v_pk_mul_f32 v[134:135], v[98:99], v[24:25]
	v_pk_add_f32 v[130:131], v[26:27], v[126:127] op_sel_hi:[1,0] neg_lo:[0,1] neg_hi:[0,1]
	v_pk_add_f32 v[132:133], v[24:25], v[126:127] op_sel_hi:[1,0] neg_lo:[0,1] neg_hi:[0,1]
	v_lshlrev_b32_e32 v128, 16, v123
	v_pk_fma_f32 v[134:135], v[96:97], v[26:27], v[134:135]
	v_pk_fma_f32 v[26:27], v[130:131], v[100:101], v[126:127] op_sel_hi:[1,1,0]
	v_pk_fma_f32 v[24:25], v[132:133], v[102:103], v[126:127] op_sel_hi:[1,1,0]
	v_add_f32_e32 v137, v134, v135
	ds_write2st64_b32 v51, v136, v137 offset0:44 offset1:45
	v_pk_mul_f32 v[134:135], v[106:107], v[24:25]
	v_pk_add_f32 v[130:131], v[26:27], v[128:129] op_sel_hi:[1,0] neg_lo:[0,1] neg_hi:[0,1]
	v_pk_add_f32 v[132:133], v[24:25], v[128:129] op_sel_hi:[1,0] neg_lo:[0,1] neg_hi:[0,1]
	v_pk_fma_f32 v[134:135], v[104:105], v[26:27], v[134:135]
	v_pk_fma_f32 v[26:27], v[130:131], v[108:109], v[128:129] op_sel_hi:[1,1,0]
	v_pk_fma_f32 v[24:25], v[132:133], v[110:111], v[128:129] op_sel_hi:[1,1,0]
	v_add_f32_e32 v138, v134, v135
	s_waitcnt lgkmcnt(1)
	v_lshlrev_b32_e32 v126, 16, v116
	v_pk_mul_f32 v[134:135], v[114:115], v[24:25]
	v_pk_add_f32 v[130:131], v[26:27], v[126:127] op_sel_hi:[1,0] neg_lo:[0,1] neg_hi:[0,1]
	v_pk_add_f32 v[132:133], v[24:25], v[126:127] op_sel_hi:[1,0] neg_lo:[0,1] neg_hi:[0,1]
	v_lshlrev_b32_e32 v128, 16, v117
	v_pk_fma_f32 v[134:135], v[112:113], v[26:27], v[134:135]
	v_pk_fma_f32 v[26:27], v[130:131], v[52:53], v[126:127] op_sel_hi:[1,1,0]
	v_pk_fma_f32 v[24:25], v[132:133], v[54:55], v[126:127] op_sel_hi:[1,1,0]
	v_add_f32_e32 v139, v134, v135
	ds_write2st64_b32 v51, v138, v139 offset0:46 offset1:47
	ds_read_u16 v120, v125 offset:2560
	ds_read_u16 v121, v125 offset:2688
	ds_read_u16 v122, v125 offset:2816
	ds_read_u16 v123, v125 offset:2944
	ds_read_b128 v[84:87], v124 offset:640
	ds_read_b128 v[88:91], v124 offset:656
	ds_read_b128 v[92:95], v124 offset:672
	ds_read_b128 v[96:99], v124 offset:688
	ds_read_b128 v[100:103], v124 offset:704
	ds_read_b128 v[104:107], v124 offset:720
	ds_read_b128 v[108:111], v124 offset:736
	ds_read_b128 v[112:115], v124 offset:752
	v_pk_mul_f32 v[134:135], v[58:59], v[24:25]
	v_pk_add_f32 v[130:131], v[26:27], v[128:129] op_sel_hi:[1,0] neg_lo:[0,1] neg_hi:[0,1]
	v_pk_add_f32 v[132:133], v[24:25], v[128:129] op_sel_hi:[1,0] neg_lo:[0,1] neg_hi:[0,1]
	v_lshlrev_b32_e32 v126, 16, v118
	v_pk_fma_f32 v[134:135], v[56:57], v[26:27], v[134:135]
	v_pk_fma_f32 v[26:27], v[130:131], v[60:61], v[128:129] op_sel_hi:[1,1,0]
	v_pk_fma_f32 v[24:25], v[132:133], v[62:63], v[128:129] op_sel_hi:[1,1,0]
	v_add_f32_e32 v136, v134, v135
	v_pk_mul_f32 v[134:135], v[66:67], v[24:25]
	v_pk_add_f32 v[130:131], v[26:27], v[126:127] op_sel_hi:[1,0] neg_lo:[0,1] neg_hi:[0,1]
	v_pk_add_f32 v[132:133], v[24:25], v[126:127] op_sel_hi:[1,0] neg_lo:[0,1] neg_hi:[0,1]
	v_lshlrev_b32_e32 v128, 16, v119
	v_pk_fma_f32 v[134:135], v[64:65], v[26:27], v[134:135]
	v_pk_fma_f32 v[26:27], v[130:131], v[68:69], v[126:127] op_sel_hi:[1,1,0]
	v_pk_fma_f32 v[24:25], v[132:133], v[70:71], v[126:127] op_sel_hi:[1,1,0]
	v_add_f32_e32 v137, v134, v135
	ds_write2st64_b32 v51, v136, v137 offset0:48 offset1:49
	v_pk_mul_f32 v[134:135], v[74:75], v[24:25]
	v_pk_add_f32 v[130:131], v[26:27], v[128:129] op_sel_hi:[1,0] neg_lo:[0,1] neg_hi:[0,1]
	v_pk_add_f32 v[132:133], v[24:25], v[128:129] op_sel_hi:[1,0] neg_lo:[0,1] neg_hi:[0,1]
	v_pk_fma_f32 v[134:135], v[72:73], v[26:27], v[134:135]
	v_pk_fma_f32 v[26:27], v[130:131], v[76:77], v[128:129] op_sel_hi:[1,1,0]
	v_pk_fma_f32 v[24:25], v[132:133], v[78:79], v[128:129] op_sel_hi:[1,1,0]
	v_add_f32_e32 v138, v134, v135
	s_waitcnt lgkmcnt(1)
	v_lshlrev_b32_e32 v126, 16, v120
	v_pk_mul_f32 v[134:135], v[82:83], v[24:25]
	v_pk_add_f32 v[130:131], v[26:27], v[126:127] op_sel_hi:[1,0] neg_lo:[0,1] neg_hi:[0,1]
	v_pk_add_f32 v[132:133], v[24:25], v[126:127] op_sel_hi:[1,0] neg_lo:[0,1] neg_hi:[0,1]
	v_lshlrev_b32_e32 v128, 16, v121
	v_pk_fma_f32 v[134:135], v[80:81], v[26:27], v[134:135]
	v_pk_fma_f32 v[26:27], v[130:131], v[84:85], v[126:127] op_sel_hi:[1,1,0]
	v_pk_fma_f32 v[24:25], v[132:133], v[86:87], v[126:127] op_sel_hi:[1,1,0]
	v_add_f32_e32 v139, v134, v135
	ds_write2st64_b32 v51, v138, v139 offset0:50 offset1:51
	ds_read_u16 v116, v125 offset:3072
	ds_read_u16 v117, v125 offset:3200
	ds_read_u16 v118, v125 offset:3328
	ds_read_u16 v119, v125 offset:3456
	ds_read_b128 v[52:55], v124 offset:768
	ds_read_b128 v[56:59], v124 offset:784
	ds_read_b128 v[60:63], v124 offset:800
	ds_read_b128 v[64:67], v124 offset:816
	ds_read_b128 v[68:71], v124 offset:832
	ds_read_b128 v[72:75], v124 offset:848
	ds_read_b128 v[76:79], v124 offset:864
	ds_read_b128 v[80:83], v124 offset:880
	v_pk_mul_f32 v[134:135], v[90:91], v[24:25]
	v_pk_add_f32 v[130:131], v[26:27], v[128:129] op_sel_hi:[1,0] neg_lo:[0,1] neg_hi:[0,1]
	v_pk_add_f32 v[132:133], v[24:25], v[128:129] op_sel_hi:[1,0] neg_lo:[0,1] neg_hi:[0,1]
	v_lshlrev_b32_e32 v126, 16, v122
	v_pk_fma_f32 v[134:135], v[88:89], v[26:27], v[134:135]
	v_pk_fma_f32 v[26:27], v[130:131], v[92:93], v[128:129] op_sel_hi:[1,1,0]
	v_pk_fma_f32 v[24:25], v[132:133], v[94:95], v[128:129] op_sel_hi:[1,1,0]
	v_add_f32_e32 v136, v134, v135
	v_pk_mul_f32 v[134:135], v[98:99], v[24:25]
	v_pk_add_f32 v[130:131], v[26:27], v[126:127] op_sel_hi:[1,0] neg_lo:[0,1] neg_hi:[0,1]
	v_pk_add_f32 v[132:133], v[24:25], v[126:127] op_sel_hi:[1,0] neg_lo:[0,1] neg_hi:[0,1]
	v_lshlrev_b32_e32 v128, 16, v123
	v_pk_fma_f32 v[134:135], v[96:97], v[26:27], v[134:135]
	v_pk_fma_f32 v[26:27], v[130:131], v[100:101], v[126:127] op_sel_hi:[1,1,0]
	v_pk_fma_f32 v[24:25], v[132:133], v[102:103], v[126:127] op_sel_hi:[1,1,0]
	v_add_f32_e32 v137, v134, v135
	ds_write2st64_b32 v51, v136, v137 offset0:52 offset1:53
	v_pk_mul_f32 v[134:135], v[106:107], v[24:25]
	v_pk_add_f32 v[130:131], v[26:27], v[128:129] op_sel_hi:[1,0] neg_lo:[0,1] neg_hi:[0,1]
	v_pk_add_f32 v[132:133], v[24:25], v[128:129] op_sel_hi:[1,0] neg_lo:[0,1] neg_hi:[0,1]
	v_pk_fma_f32 v[134:135], v[104:105], v[26:27], v[134:135]
	v_pk_fma_f32 v[26:27], v[130:131], v[108:109], v[128:129] op_sel_hi:[1,1,0]
	v_pk_fma_f32 v[24:25], v[132:133], v[110:111], v[128:129] op_sel_hi:[1,1,0]
	v_add_f32_e32 v138, v134, v135
	s_waitcnt lgkmcnt(1)
	v_lshlrev_b32_e32 v126, 16, v116
	v_pk_mul_f32 v[134:135], v[114:115], v[24:25]
	v_pk_add_f32 v[130:131], v[26:27], v[126:127] op_sel_hi:[1,0] neg_lo:[0,1] neg_hi:[0,1]
	v_pk_add_f32 v[132:133], v[24:25], v[126:127] op_sel_hi:[1,0] neg_lo:[0,1] neg_hi:[0,1]
	v_lshlrev_b32_e32 v128, 16, v117
	v_pk_fma_f32 v[134:135], v[112:113], v[26:27], v[134:135]
	v_pk_fma_f32 v[26:27], v[130:131], v[52:53], v[126:127] op_sel_hi:[1,1,0]
	v_pk_fma_f32 v[24:25], v[132:133], v[54:55], v[126:127] op_sel_hi:[1,1,0]
	v_add_f32_e32 v139, v134, v135
	ds_write2st64_b32 v51, v138, v139 offset0:54 offset1:55
	ds_read_u16 v120, v125 offset:3584
	ds_read_u16 v121, v125 offset:3712
	ds_read_u16 v122, v125 offset:3840
	ds_read_u16 v123, v125 offset:3968
	ds_read_b128 v[84:87], v124 offset:896
	ds_read_b128 v[88:91], v124 offset:912
	ds_read_b128 v[92:95], v124 offset:928
	ds_read_b128 v[96:99], v124 offset:944
	ds_read_b128 v[100:103], v124 offset:960
	ds_read_b128 v[104:107], v124 offset:976
	ds_read_b128 v[108:111], v124 offset:992
	ds_read_b128 v[112:115], v124 offset:1008
	v_pk_mul_f32 v[134:135], v[58:59], v[24:25]
	v_pk_add_f32 v[130:131], v[26:27], v[128:129] op_sel_hi:[1,0] neg_lo:[0,1] neg_hi:[0,1]
	v_pk_add_f32 v[132:133], v[24:25], v[128:129] op_sel_hi:[1,0] neg_lo:[0,1] neg_hi:[0,1]
	v_lshlrev_b32_e32 v126, 16, v118
	v_pk_fma_f32 v[134:135], v[56:57], v[26:27], v[134:135]
	v_pk_fma_f32 v[26:27], v[130:131], v[60:61], v[128:129] op_sel_hi:[1,1,0]
	v_pk_fma_f32 v[24:25], v[132:133], v[62:63], v[128:129] op_sel_hi:[1,1,0]
	v_add_f32_e32 v136, v134, v135
	v_pk_mul_f32 v[134:135], v[66:67], v[24:25]
	v_pk_add_f32 v[130:131], v[26:27], v[126:127] op_sel_hi:[1,0] neg_lo:[0,1] neg_hi:[0,1]
	v_pk_add_f32 v[132:133], v[24:25], v[126:127] op_sel_hi:[1,0] neg_lo:[0,1] neg_hi:[0,1]
	v_lshlrev_b32_e32 v128, 16, v119
	v_pk_fma_f32 v[134:135], v[64:65], v[26:27], v[134:135]
	v_pk_fma_f32 v[26:27], v[130:131], v[68:69], v[126:127] op_sel_hi:[1,1,0]
	v_pk_fma_f32 v[24:25], v[132:133], v[70:71], v[126:127] op_sel_hi:[1,1,0]
	v_add_f32_e32 v137, v134, v135
	ds_write2st64_b32 v51, v136, v137 offset0:56 offset1:57
	v_pk_mul_f32 v[134:135], v[74:75], v[24:25]
	v_pk_add_f32 v[130:131], v[26:27], v[128:129] op_sel_hi:[1,0] neg_lo:[0,1] neg_hi:[0,1]
	v_pk_add_f32 v[132:133], v[24:25], v[128:129] op_sel_hi:[1,0] neg_lo:[0,1] neg_hi:[0,1]
	v_pk_fma_f32 v[134:135], v[72:73], v[26:27], v[134:135]
	v_pk_fma_f32 v[26:27], v[130:131], v[76:77], v[128:129] op_sel_hi:[1,1,0]
	v_pk_fma_f32 v[24:25], v[132:133], v[78:79], v[128:129] op_sel_hi:[1,1,0]
	v_add_f32_e32 v138, v134, v135
	s_waitcnt lgkmcnt(1)
	v_lshlrev_b32_e32 v126, 16, v120
	v_pk_mul_f32 v[134:135], v[82:83], v[24:25]
	v_pk_add_f32 v[130:131], v[26:27], v[126:127] op_sel_hi:[1,0] neg_lo:[0,1] neg_hi:[0,1]
	v_pk_add_f32 v[132:133], v[24:25], v[126:127] op_sel_hi:[1,0] neg_lo:[0,1] neg_hi:[0,1]
	v_lshlrev_b32_e32 v128, 16, v121
	v_pk_fma_f32 v[134:135], v[80:81], v[26:27], v[134:135]
	v_pk_fma_f32 v[26:27], v[130:131], v[84:85], v[126:127] op_sel_hi:[1,1,0]
	v_pk_fma_f32 v[24:25], v[132:133], v[86:87], v[126:127] op_sel_hi:[1,1,0]
	v_add_f32_e32 v139, v134, v135
	ds_write2st64_b32 v51, v138, v139 offset0:58 offset1:59
	v_pk_mul_f32 v[134:135], v[90:91], v[24:25]
	v_pk_add_f32 v[130:131], v[26:27], v[128:129] op_sel_hi:[1,0] neg_lo:[0,1] neg_hi:[0,1]
	v_pk_add_f32 v[132:133], v[24:25], v[128:129] op_sel_hi:[1,0] neg_lo:[0,1] neg_hi:[0,1]
	v_lshlrev_b32_e32 v126, 16, v122
	v_pk_fma_f32 v[134:135], v[88:89], v[26:27], v[134:135]
	v_pk_fma_f32 v[26:27], v[130:131], v[92:93], v[128:129] op_sel_hi:[1,1,0]
	v_pk_fma_f32 v[24:25], v[132:133], v[94:95], v[128:129] op_sel_hi:[1,1,0]
	v_add_f32_e32 v136, v134, v135
	v_pk_mul_f32 v[134:135], v[98:99], v[24:25]
	v_pk_add_f32 v[130:131], v[26:27], v[126:127] op_sel_hi:[1,0] neg_lo:[0,1] neg_hi:[0,1]
	v_pk_add_f32 v[132:133], v[24:25], v[126:127] op_sel_hi:[1,0] neg_lo:[0,1] neg_hi:[0,1]
	v_lshlrev_b32_e32 v128, 16, v123
	v_pk_fma_f32 v[134:135], v[96:97], v[26:27], v[134:135]
	v_pk_fma_f32 v[26:27], v[130:131], v[100:101], v[126:127] op_sel_hi:[1,1,0]
	v_pk_fma_f32 v[24:25], v[132:133], v[102:103], v[126:127] op_sel_hi:[1,1,0]
	v_add_f32_e32 v137, v134, v135
	ds_write2st64_b32 v51, v136, v137 offset0:60 offset1:61
	v_pk_mul_f32 v[134:135], v[106:107], v[24:25]
	v_pk_add_f32 v[130:131], v[26:27], v[128:129] op_sel_hi:[1,0] neg_lo:[0,1] neg_hi:[0,1]
	v_pk_add_f32 v[132:133], v[24:25], v[128:129] op_sel_hi:[1,0] neg_lo:[0,1] neg_hi:[0,1]
	v_pk_fma_f32 v[134:135], v[104:105], v[26:27], v[134:135]
	v_pk_fma_f32 v[26:27], v[130:131], v[108:109], v[128:129] op_sel_hi:[1,1,0]
	v_pk_fma_f32 v[24:25], v[132:133], v[110:111], v[128:129] op_sel_hi:[1,1,0]
	v_add_f32_e32 v138, v134, v135
	v_pk_mul_f32 v[134:135], v[114:115], v[24:25]
	s_nop 0
	v_pk_fma_f32 v[134:135], v[112:113], v[26:27], v[134:135]
	s_nop 0
	v_add_f32_e32 v139, v134, v135
	ds_write2st64_b32 v51, v138, v139 offset0:62 offset1:63
	s_cmp_lg_u32 s23, 3
	s_cbranch_scc1 .Lhg_mstage_skip
	s_andn2_b64 vcc, exec, s[14:15]
	s_cbranch_vccnz .Lhg_mstage_skip
	s_and_b32 s41, s22, 1
	s_lshl_b32 s46, s41, 14
	s_xor_b32 s46, s46, 0x4000
	s_lshl_b32 s41, s41, 12
	v_add_u32_e32 v48, s46, v15
	s_xor_b32 s41, s41, 0x1000
	s_waitcnt vmcnt(2)
	ds_write_b128 v48, v[0:3]
	s_waitcnt vmcnt(1)
	ds_write_b128 v48, v[4:7] offset:8192
	v_add_u32_e32 v48, s41, v29
	s_waitcnt vmcnt(0)
	ds_write_b128 v48, v[8:11]

.Lhg_helper:
	s_cmp_eq_u32 s23, 3
	s_cbranch_scc1 .Lhg_hstage
	v_add_u32_e32 v48, 0x3e0, v46
	v_add_u32_e32 v50, 0x3e0, v45
	v_add_u32_e32 v49, 0x1c000, v48
	v_add_u32_e32 v51, 0x1a200, v50
	v_add_u32_e32 v52, 0x1c200, v50
	v_add_u32_e32 v48, 0x1a000, v48
	ds_read_u16 v49, v49
	ds_read_u16 v51, v51
	ds_read_u16 v52, v52
	ds_read_u16 v48, v48
	s_xor_b32 s41, s40, 1
	s_lshl_b32 s41, s41, 12
	s_waitcnt lgkmcnt(3)
	v_lshlrev_b32_e32 v49, 16, v49
	v_mul_f32_e64 v53, |v49|, s83
	v_exp_f32_e32 v53, v53
	v_cmp_le_f32_e32 vcc, 0, v49
	s_waitcnt lgkmcnt(0)
	v_lshlrev_b32_e32 v48, 16, v48
	v_lshlrev_b32_e32 v52, 16, v52
	v_add_f32_e32 v54, 1.0, v53
	v_rcp_f32_e32 v54, v54
	v_mul_f32_e64 v55, |v52|, s83
	v_exp_f32_e32 v55, v55
	v_lshlrev_b32_e32 v51, 16, v51
	v_mul_f32_e32 v53, v53, v54
	v_cndmask_b32_e32 v49, v53, v54, vcc
	v_mul_f32_e32 v54, 0xbfb8aa3b, v48
	v_exp_f32_e32 v54, v54
	v_mul_f32_e32 v57, 0xbfb8aa3b, v51
	v_exp_f32_e32 v57, v57
	v_add_f32_e32 v56, 1.0, v55
	v_add_f32_e32 v54, 1.0, v54
	v_rcp_f32_e32 v54, v54
	v_fma_f32 v49, v31, v49, v23
	v_add3_u32 v53, v30, v33, s41
	v_rcp_f32_e32 v56, v56
	v_mul_f32_e32 v48, v54, v48
	ds_write2_b32 v53, v49, v48 offset1:4
	v_add_f32_e32 v49, 1.0, v57
	v_rcp_f32_e32 v49, v49
	v_mul_f32_e32 v48, v55, v56
	v_cmp_le_f32_e32 vcc, 0, v52
	v_add_u32_e32 v52, s41, v37
	v_mul_f32_e32 v49, v49, v51
	v_cndmask_b32_e32 v48, v48, v56, vcc
	v_fma_f32 v48, v31, v48, v23
	ds_write2_b32 v52, v48, v49 offset1:4
	s_branch .LBB0_820
.Lhg_hstage:
	s_andn2_b64 vcc, exec, s[14:15]
	s_cbranch_vccnz .LBB0_820
	s_and_b32 s41, s22, 1
	s_lshl_b32 s46, s41, 14
	s_xor_b32 s46, s46, 0x4000
	s_lshl_b32 s41, s41, 12
	v_add_u32_e32 v48, s46, v15
	s_xor_b32 s41, s41, 0x1000
	s_waitcnt vmcnt(2)
	ds_write_b128 v48, v[0:3]
	s_waitcnt vmcnt(1)
	ds_write_b128 v48, v[4:7] offset:8192
	v_add_u32_e32 v48, s41, v29
	s_waitcnt vmcnt(0)
	ds_write_b128 v48, v[8:11]

.LBB0_822:
	s_andn2_b64 vcc, exec, s[14:15]
	s_branch .LBB0_824
